# attention main loop: K-fragment ds_reads of QK^T batched 4 deep with counted lgkmcnt (v010 base)
# baseline (speedup 1.0000x reference)
; #define MFMA32(a, b, c) __builtin_amdgcn_mfma_f32_32x32x16_bf16((a), (b), (c), 0, 0, 0)
; DI s16x4 vtr(lds_cptr p) { return __builtin_bit_cast(s16x4, __builtin_amdgcn_ds_read_tr16_b64_v4i16((LAS v4i16_t*)p)); }
; DI void finishSM(f32x16& p0, f32x16& p1, float alpha, float& l_reg, s16x8& pa0, s16x8& pa1, s16x8& pa2, s16x8& pa3) {
; #pragma unroll
;   for (int r = 0; r < 16; ++r) p1[r] = __builtin_amdgcn_exp2f(p1[r]);
;   float ps = 0;
; #pragma unroll
;   for (int r = 0; r < 16; ++r) ps += p0[r];
; #pragma unroll
;   for (int r = 0; r < 16; ++r) ps += p1[r];
;   { auto rr = __builtin_amdgcn_permlane32_swap(__float_as_uint(ps), __float_as_uint(ps), false, false);
;     ps = __uint_as_float(rr[0]) + __uint_as_float(rr[1]); }
;   l_reg = l_reg * alpha + ps;
;   PK4(p0, 0, pa0); PK4(p0, 8, pa1); PK4(p1, 0, pa2); PK4(p1, 8, pa3);
; }
; DI void qkt64(f32x16& p0, f32x16& p1, const char* Ks, const s16x8* qr, const f32x16& negm, int comp, int r32, int hi) {
; #pragma unroll
;   for (int d0 = 0; d0 < 4; ++d0) { const int cb = (comp * 64 + d0 * 16 + hi * 8) * 2;
;     const s16x8 b0 = *(const s16x8*)(Ks + KSWZ(r32, cb));
;     const s16x8 b1 = *(const s16x8*)(Ks + KSWZ(32 + r32, cb));
;     if (d0 == 0) { p0 = MFMA32(b0, qr[0], negm); p1 = MFMA32(b1, qr[0], negm); }
;     else { p0 = MFMA32(b0, qr[d0], p0); p1 = MFMA32(b1, qr[d0], p1); } }
; }
; DI void pv_all(f32x16* o, int vb, s16x8 pa0, s16x8 pa1, s16x8 pa2, s16x8 pa3) {
;   const lds_cptr p = (lds_cptr)(uintptr_t)(unsigned)vb;
;   const s16x8 pa[4] = {pa0, pa1, pa2, pa3};
; #pragma unroll
;   for (int ks = 0; ks < 4; ++ks)
; #pragma unroll
;     for (int d0 = 0; d0 < 4; ++d0) { const s16x4 l = vtr(p + v_rd_off(d0, ks, 0)), h = vtr(p + v_rd_off(d0, ks, 1)); o[d0] = MFMA32(pa[ks], PKF(l, h), o[d0]); }
; }
; template <int AV_> DI void attn_unit(const u16* __restrict__ Qb, u16* __restrict__ Ob, const u16* __restrict__ Kh, const u16* __restrict__ Vh, float lam, const float* __restrict__ subw, char* lds) {
;     ...
;   for (int j = 1; j + 1 < NT; j += 2) {
;     SDMA((j + 1) * 64, 0, vnext);
;     qkt64(pB0, pB1, K_lds + SHM_K, qr, negm, comp, r32, hi);
;     finishSM(pA0, pA1, alA, l_reg, pa0, pa1, pa2, pa3);
;     pv_all(o, vb0 + vprev * SHM_V, pa0, pa1, pa2, pa3);
.LBB0_380:
	s_lshl_b32 s46, s66, 14
	v_lshl_add_u64 v[146:147], v[186:187], 0, v[184:185]
	s_mov_b32 m0, s1
	v_lshl_add_u64 v[66:67], v[146:147], 0, s[18:19]
	v_lshl_add_u64 v[148:149], v[188:189], 0, v[184:185]
	s_add_i32 s46, s0, s46
	global_load_lds_dwordx4 v[66:67], off
	v_lshl_add_u64 v[66:67], v[148:149], 0, s[20:21]
	s_mov_b32 m0, s46
	v_lshl_add_u64 v[150:151], v[190:191], 0, v[184:185]
	global_load_lds_dwordx4 v[66:67], off
	v_lshl_add_u64 v[66:67], v[150:151], 0, s[18:19]
	s_mov_b32 m0, s2
	v_lshl_add_u64 v[152:153], v[192:193], 0, v[184:185]
	global_load_lds_dwordx4 v[66:67], off
	v_lshl_add_u64 v[66:67], v[152:153], 0, s[20:21]
	s_add_i32 m0, s46, 0x2000
	v_add_u32_e32 v211, s56, v200
	global_load_lds_dwordx4 v[66:67], off
	v_add_u32_e32 v0, s56, v202
	v_add_u32_e32 v212, s56, v204
	v_add_u32_e32 v213, s56, v206
	ds_read_b128 v[66:69], v211
	ds_read_b128 v[70:73], v211 offset:8192
	ds_read_b128 v[74:77], v0
	ds_read_b128 v[78:81], v0 offset:8192
	v_lshl_add_u32 v230, s65, 14, v210
	v_exp_f32_e32 v158, v98
	v_exp_f32_e32 v159, v99
	v_exp_f32_e32 v160, v100
	v_exp_f32_e32 v161, v101
	s_waitcnt lgkmcnt(3)
	v_mfma_f32_32x32x16_bf16 v[130:145], v[66:69], v[174:177], v[82:97]
	v_exp_f32_e32 v214, v102
	v_exp_f32_e32 v215, v103
	s_waitcnt lgkmcnt(2)
	v_mfma_f32_32x32x16_bf16 v[114:129], v[70:73], v[174:177], v[82:97]
	ds_read_b128 v[66:69], v212
	v_exp_f32_e32 v216, v104
	v_exp_f32_e32 v229, v105
	v_exp_f32_e32 v106, v106
	s_waitcnt lgkmcnt(2)
	v_mfma_f32_32x32x16_bf16 v[130:145], v[74:77], v[170:173], v[130:145]
	ds_read_b128 v[70:73], v212 offset:8192
	v_exp_f32_e32 v107, v107
	v_exp_f32_e32 v108, v108
	v_exp_f32_e32 v109, v109
	s_waitcnt lgkmcnt(2)
	v_mfma_f32_32x32x16_bf16 v[114:129], v[78:81], v[170:173], v[114:129]
	ds_read_b128 v[74:77], v213 offset:8192
	ds_read_b128 v[78:81], v213
	v_exp_f32_e32 v110, v110
	v_exp_f32_e32 v111, v111
	v_exp_f32_e32 v112, v112
	v_exp_f32_e32 v113, v113
	s_waitcnt lgkmcnt(0)
	v_mfma_f32_32x32x16_bf16 v[130:145], v[66:69], v[166:169], v[130:145]
	v_cvt_pk_bf16_f32 v66, v228, v227
	v_cvt_pk_bf16_f32 v67, v222, v223
	v_cvt_pk_bf16_f32 v68, v224, v225
	v_cvt_pk_bf16_f32 v69, v226, v221
	s_nop 0
	v_permlane32_swap_b32_e32 v66, v68
	v_permlane32_swap_b32_e32 v67, v69
	v_mfma_f32_32x32x16_bf16 v[114:129], v[70:73], v[166:169], v[114:129]
	ds_read_b64_tr_b16 v[72:73], v230 offset:2048
	v_mfma_f32_32x32x16_bf16 v[130:145], v[78:81], v[162:165], v[130:145]
	v_mfma_f32_32x32x16_bf16 v[114:129], v[74:77], v[162:165], v[114:129]
	ds_read_b64_tr_b16 v[70:71], v230
	ds_read_b64_tr_b16 v[74:75], v230 offset:512
	ds_read_b64_tr_b16 v[78:79], v230 offset:1024
	ds_read_b64_tr_b16 v[98:99], v230 offset:1536
	ds_read_b64_tr_b16 v[76:77], v230 offset:2560
	ds_read_b64_tr_b16 v[80:81], v230 offset:3072
	ds_read_b64_tr_b16 v[100:101], v230 offset:3584
	s_waitcnt lgkmcnt(0)
	v_mfma_f32_32x32x16_bf16 v[50:65], v[66:69], v[70:73], v[50:65]
	v_add_f32_e32 v70, 0, v228
	v_add_f32_e32 v70, v227, v70
	v_add_f32_e32 v70, v222, v70
	v_add_f32_e32 v70, v223, v70
	v_add_f32_e32 v70, v224, v70
	v_add_f32_e32 v70, v225, v70
	v_add_f32_e32 v102, v226, v70
	v_cvt_pk_bf16_f32 v70, v217, v218
	v_cvt_pk_bf16_f32 v71, v219, v220
	v_cvt_pk_bf16_f32 v72, v157, v155
	v_cvt_pk_bf16_f32 v73, v154, v156
	v_mfma_f32_32x32x16_bf16 v[34:49], v[66:69], v[74:77], v[34:49]
	v_permlane32_swap_b32_e32 v70, v72
	v_permlane32_swap_b32_e32 v71, v73
	ds_read_b64_tr_b16 v[76:77], v230 offset:6144
	v_mfma_f32_32x32x16_bf16 v[18:33], v[66:69], v[78:81], v[18:33]
	v_mfma_f32_32x32x16_bf16 v[2:17], v[66:69], v[98:101], v[2:17]
	ds_read_b64_tr_b16 v[74:75], v230 offset:4096
	ds_read_b64_tr_b16 v[66:67], v230 offset:4608
	ds_read_b64_tr_b16 v[78:79], v230 offset:5120
	ds_read_b64_tr_b16 v[98:99], v230 offset:5632
	ds_read_b64_tr_b16 v[68:69], v230 offset:6656
	ds_read_b64_tr_b16 v[80:81], v230 offset:7168
	ds_read_b64_tr_b16 v[100:101], v230 offset:7680
	s_waitcnt lgkmcnt(0)
; DI void partialSM(f32x16& p0, f32x16& p1, float& m_reg, f32x16& negm, float& alpha) {
;   float pmax = fmaxf(p0[0], p0[1]);
; #pragma unroll
;   for (int r = 2; r < 16; ++r) pmax = fmaxf(pmax, p0[r]);
; #pragma unroll
;   for (int r = 0; r < 16; ++r) pmax = fmaxf(pmax, p1[r]);
;   { auto rr = __builtin_amdgcn_permlane32_swap(__float_as_uint(pmax), __float_as_uint(pmax), false, false);
;     pmax = fmaxf(__uint_as_float(rr[0]), __uint_as_float(rr[1])); }
;   alpha = 1.f;
;   if (__builtin_expect(!__all(pmax <= ATT_THR), 0)) {
;     const float dl = fmaxf(pmax, 0.f); m_reg += dl; alpha = __builtin_amdgcn_exp2f(-dl);
; #pragma unroll
;     for (int r = 0; r < 16; ++r) { p0[r] -= dl; p1[r] -= dl; negm[r] = -m_reg; }
;   }
; #pragma unroll
;   for (int r = 0; r < 16; ++r) p0[r] = __builtin_amdgcn_exp2f(p0[r]);
; }
; DI void finishSM(f32x16& p0, f32x16& p1, float alpha, float& l_reg, s16x8& pa0, s16x8& pa1, s16x8& pa2, s16x8& pa3) {
; #pragma unroll
;   for (int r = 0; r < 16; ++r) p1[r] = __builtin_amdgcn_exp2f(p1[r]);
;   float ps = 0;
; #pragma unroll
;   for (int r = 0; r < 16; ++r) ps += p0[r];
; #pragma unroll
;   for (int r = 0; r < 16; ++r) ps += p1[r];
;   { auto rr = __builtin_amdgcn_permlane32_swap(__float_as_uint(ps), __float_as_uint(ps), false, false);
;     ps = __uint_as_float(rr[0]) + __uint_as_float(rr[1]); }
;   l_reg = l_reg * alpha + ps;
;   PK4(p0, 0, pa0); PK4(p0, 8, pa1); PK4(p1, 0, pa2); PK4(p1, 8, pa3);
; }
; DI void qkt64(f32x16& p0, f32x16& p1, const char* Ks, const s16x8* qr, const f32x16& negm, int comp, int r32, int hi) {
; #pragma unroll
;   for (int d0 = 0; d0 < 4; ++d0) { const int cb = (comp * 64 + d0 * 16 + hi * 8) * 2;
;     const s16x8 b0 = *(const s16x8*)(Ks + KSWZ(r32, cb));
;     const s16x8 b1 = *(const s16x8*)(Ks + KSWZ(32 + r32, cb));
;     if (d0 == 0) { p0 = MFMA32(b0, qr[0], negm); p1 = MFMA32(b1, qr[0], negm); }
;     else { p0 = MFMA32(b0, qr[d0], p0); p1 = MFMA32(b1, qr[d0], p1); } }
; }
; DI void pv_all(f32x16* o, int vb, s16x8 pa0, s16x8 pa1, s16x8 pa2, s16x8 pa3) {
;   const lds_cptr p = (lds_cptr)(uintptr_t)(unsigned)vb;
;   const s16x8 pa[4] = {pa0, pa1, pa2, pa3};
; #pragma unroll
;   for (int ks = 0; ks < 4; ++ks)
; #pragma unroll
;     for (int d0 = 0; d0 < 4; ++d0) { const s16x4 l = vtr(p + v_rd_off(d0, ks, 0)), h = vtr(p + v_rd_off(d0, ks, 1)); o[d0] = MFMA32(pa[ks], PKF(l, h), o[d0]); }
; }
	v_mfma_f32_32x32x16_bf16 v[50:65], v[70:73], v[74:77], v[50:65]
	v_add_f32_e32 v74, v221, v102
	v_add_f32_e32 v74, v217, v74
	v_add_f32_e32 v74, v218, v74
	v_add_f32_e32 v74, v219, v74
	v_add_f32_e32 v74, v220, v74
	v_add_f32_e32 v74, v157, v74
	v_add_f32_e32 v74, v155, v74
	v_mfma_f32_32x32x16_bf16 v[34:49], v[70:73], v[66:69], v[34:49]
	v_add_f32_e32 v66, v154, v74
	v_add_f32_e32 v66, v156, v66
	v_add_f32_e32 v66, v158, v66
	v_add_f32_e32 v66, v159, v66
	v_add_f32_e32 v154, v160, v66
	v_cvt_pk_bf16_f32 v66, v158, v159
	v_cvt_pk_bf16_f32 v67, v160, v161
	v_mfma_f32_32x32x16_bf16 v[18:33], v[70:73], v[78:81], v[18:33]
	v_cvt_pk_bf16_f32 v68, v214, v215
	v_cvt_pk_bf16_f32 v69, v216, v229
	s_nop 0
	v_permlane32_swap_b32_e32 v66, v68
	v_permlane32_swap_b32_e32 v67, v69
	ds_read_b64_tr_b16 v[74:75], v230 offset:10240
	v_mfma_f32_32x32x16_bf16 v[2:17], v[70:73], v[98:101], v[2:17]
	v_add_f32_e32 v70, v161, v154
	v_add_f32_e32 v70, v214, v70
	v_add_f32_e32 v70, v215, v70
	v_add_f32_e32 v70, v216, v70
	v_add_f32_e32 v70, v229, v70
	v_add_f32_e32 v70, v106, v70
	v_add_f32_e32 v70, v107, v70
	v_add_f32_e32 v70, v108, v70
	ds_read_b64_tr_b16 v[72:73], v230 offset:8192
	ds_read_b64_tr_b16 v[76:77], v230 offset:8704
	ds_read_b64_tr_b16 v[98:99], v230 offset:9216
	ds_read_b64_tr_b16 v[102:103], v230 offset:9728
	ds_read_b64_tr_b16 v[78:79], v230 offset:10752
	ds_read_b64_tr_b16 v[100:101], v230 offset:11264
	ds_read_b64_tr_b16 v[104:105], v230 offset:11776
	v_add_f32_e32 v70, v109, v70
	s_waitcnt lgkmcnt(0)
	v_mfma_f32_32x32x16_bf16 v[50:65], v[66:69], v[72:75], v[50:65]
	v_add_f32_e32 v70, v110, v70
	v_add_f32_e32 v70, v111, v70
	v_add_f32_e32 v154, v112, v70
	v_cvt_pk_bf16_f32 v70, v106, v107
	v_cvt_pk_bf16_f32 v71, v108, v109
	v_cvt_pk_bf16_f32 v72, v110, v111
	v_cvt_pk_bf16_f32 v73, v112, v113
	v_mfma_f32_32x32x16_bf16 v[34:49], v[66:69], v[76:79], v[34:49]
	v_permlane32_swap_b32_e32 v70, v72
	v_permlane32_swap_b32_e32 v71, v73
	ds_read_b64_tr_b16 v[76:77], v230 offset:14336
	v_add_f32_e32 v214, v113, v154
	v_mov_b32_e32 v215, v214
	v_mfma_f32_32x32x16_bf16 v[18:33], v[66:69], v[98:101], v[18:33]
	s_nop 0
	v_permlane32_swap_b32_e32 v214, v215
	v_mfma_f32_32x32x16_bf16 v[2:17], v[66:69], v[102:105], v[2:17]
	ds_read_b64_tr_b16 v[74:75], v230 offset:12288
	ds_read_b64_tr_b16 v[66:67], v230 offset:12800
	ds_read_b64_tr_b16 v[78:79], v230 offset:13312
	ds_read_b64_tr_b16 v[98:99], v230 offset:13824
	ds_read_b64_tr_b16 v[68:69], v230 offset:14848
	ds_read_b64_tr_b16 v[80:81], v230 offset:15360
	ds_read_b64_tr_b16 v[100:101], v230 offset:15872
	s_waitcnt lgkmcnt(0)
	v_mfma_f32_32x32x16_bf16 v[50:65], v[70:73], v[74:77], v[50:65]
	v_max_f32_e32 v74, v131, v131
	v_max_f32_e32 v75, v130, v130
	v_max_f32_e32 v74, v75, v74
	v_mfma_f32_32x32x16_bf16 v[34:49], v[70:73], v[66:69], v[34:49]
	v_max3_f32 v66, v74, v132, v133
	v_max3_f32 v66, v66, v134, v135
	v_max3_f32 v66, v66, v136, v137
	v_max3_f32 v66, v66, v138, v139
	v_max3_f32 v66, v66, v140, v141
	v_max3_f32 v66, v66, v142, v143
	v_max3_f32 v66, v66, v144, v145
	v_max3_f32 v66, v66, v114, v115
	v_max3_f32 v66, v66, v116, v117
	v_max3_f32 v66, v66, v118, v119
	v_max3_f32 v66, v66, v120, v121
	v_max3_f32 v66, v66, v122, v123
	v_max3_f32 v66, v66, v124, v125
	v_mfma_f32_32x32x16_bf16 v[18:33], v[70:73], v[78:81], v[18:33]
	v_max3_f32 v66, v66, v126, v127
	v_max3_f32 v66, v66, v128, v129
	v_mov_b32_e32 v67, v66
	s_nop 1
	v_permlane32_swap_b32_e32 v66, v67
	v_max_f32_e32 v67, v67, v67
	v_max_f32_e32 v66, v66, v66
	v_mfma_f32_32x32x16_bf16 v[2:17], v[70:73], v[98:101], v[2:17]
	v_max_f32_e32 v66, v66, v67
	v_cmp_ge_f32_e32 vcc, s58, v66
	s_cmp_eq_u64 vcc, exec
	s_cbranch_scc0 .LBB0_392
	v_mov_b64_e32 v[66:67], v[82:83]
	v_mov_b32_e32 v216, 1.0
	v_mov_b64_e32 v[68:69], v[84:85]
	v_mov_b64_e32 v[70:71], v[86:87]
	v_mov_b64_e32 v[72:73], v[88:89]
	v_mov_b64_e32 v[74:75], v[90:91]
	v_mov_b64_e32 v[76:77], v[92:93]
	v_mov_b64_e32 v[78:79], v[94:95]
	v_mov_b64_e32 v[80:81], v[96:97]
	v_cmp_gt_f32_e32 vcc, 1.0, v216
	s_cbranch_vccz .LBB0_385

; #define MFMA32(a, b, c) __builtin_amdgcn_mfma_f32_32x32x16_bf16((a), (b), (c), 0, 0, 0)
; DI s16x4 vtr(lds_cptr p) { return __builtin_bit_cast(s16x4, __builtin_amdgcn_ds_read_tr16_b64_v4i16((LAS v4i16_t*)p)); }
; #define SLAND() asm volatile("s_waitcnt vmcnt(0)" ::: "memory")
; #define VROT() do { vprev = (vprev == 2) ? 0 : vprev + 1; vnext = (vnext == 2) ? 0 : vnext + 1; } while (0)
; DI void finishSM(f32x16& p0, f32x16& p1, float alpha, float& l_reg, s16x8& pa0, s16x8& pa1, s16x8& pa2, s16x8& pa3) {
; #pragma unroll
;   for (int r = 0; r < 16; ++r) p1[r] = __builtin_amdgcn_exp2f(p1[r]);
;   float ps = 0;
; #pragma unroll
;   for (int r = 0; r < 16; ++r) ps += p0[r];
; #pragma unroll
;   for (int r = 0; r < 16; ++r) ps += p1[r];
;   { auto rr = __builtin_amdgcn_permlane32_swap(__float_as_uint(ps), __float_as_uint(ps), false, false);
;     ps = __uint_as_float(rr[0]) + __uint_as_float(rr[1]); }
;   l_reg = l_reg * alpha + ps;
;   PK4(p0, 0, pa0); PK4(p0, 8, pa1); PK4(p1, 0, pa2); PK4(p1, 8, pa3);
; }
; DI void qkt64(f32x16& p0, f32x16& p1, const char* Ks, const s16x8* qr, const f32x16& negm, int comp, int r32, int hi) {
; #pragma unroll
;   for (int d0 = 0; d0 < 4; ++d0) { const int cb = (comp * 64 + d0 * 16 + hi * 8) * 2;
;     const s16x8 b0 = *(const s16x8*)(Ks + KSWZ(r32, cb));
;     const s16x8 b1 = *(const s16x8*)(Ks + KSWZ(32 + r32, cb));
;     if (d0 == 0) { p0 = MFMA32(b0, qr[0], negm); p1 = MFMA32(b1, qr[0], negm); }
;     else { p0 = MFMA32(b0, qr[d0], p0); p1 = MFMA32(b1, qr[d0], p1); } }
; }
; DI void pv_all(f32x16* o, int vb, s16x8 pa0, s16x8 pa1, s16x8 pa2, s16x8 pa3) {
;   const lds_cptr p = (lds_cptr)(uintptr_t)(unsigned)vb;
;   const s16x8 pa[4] = {pa0, pa1, pa2, pa3};
; #pragma unroll
;   for (int ks = 0; ks < 4; ++ks)
; #pragma unroll
;     for (int d0 = 0; d0 < 4; ++d0) { const s16x4 l = vtr(p + v_rd_off(d0, ks, 0)), h = vtr(p + v_rd_off(d0, ks, 1)); o[d0] = MFMA32(pa[ks], PKF(l, h), o[d0]); }
; }
; template <int AV_> DI void attn_unit(const u16* __restrict__ Qb, u16* __restrict__ Ob, const u16* __restrict__ Kh, const u16* __restrict__ Vh, float lam, const float* __restrict__ subw, char* lds) {
;     ...
;     SLAND(); VROT(); __syncthreads();
;     if (j + 2 < NT) SDMA((j + 2) * 64, 1, vnext);
;     qkt64(pA0, pA1, K_lds, qr, negm, comp, r32, hi);
.LBB0_385:
	s_add_i32 s46, s65, 1
	s_cmp_lg_u32 s65, 2
	s_cselect_b32 s65, s46, 0
	s_add_i32 s46, s66, 1
	s_cmp_lg_u32 s66, 2
	s_cselect_b32 s66, s46, 0
	s_lshl_b32 s46, s66, 14
	s_mov_b32 m0, s3
	v_lshl_add_u64 v[98:99], v[146:147], 0, s[22:23]
	s_add_i32 s46, s0, s46
	s_waitcnt vmcnt(0)
	s_waitcnt vmcnt(0)
	s_barrier
	global_load_lds_dwordx4 v[98:99], off
	v_lshl_add_u64 v[98:99], v[148:149], 0, s[24:25]
	s_mov_b32 m0, s46
	v_exp_f32_e32 v217, v130
	global_load_lds_dwordx4 v[98:99], off
	v_lshl_add_u64 v[98:99], v[150:151], 0, s[22:23]
	s_mov_b32 m0, s33
	v_exp_f32_e32 v230, v131
	global_load_lds_dwordx4 v[98:99], off
	v_lshl_add_u64 v[98:99], v[152:153], 0, s[24:25]
	s_add_i32 m0, s46, 0x2000
	v_exp_f32_e32 v231, v132
	global_load_lds_dwordx4 v[98:99], off
	ds_read_b128 v[98:101], v201 offset:49152
	ds_read_b128 v[218:221], v201 offset:57344
	ds_read_b128 v[222:225], v203 offset:49152
	ds_read_b128 v[226:229], v203 offset:57344
	s_waitcnt lgkmcnt(3)
	v_mfma_f32_32x32x16_bf16 v[146:161], v[98:101], v[174:177], v[66:81]
	v_exp_f32_e32 v232, v133
	v_exp_f32_e32 v233, v134
	v_exp_f32_e32 v234, v135
	v_exp_f32_e32 v235, v136
	v_exp_f32_e32 v236, v137
	v_cvt_pk_bf16_f32 v134, v217, v230
	v_cvt_pk_bf16_f32 v135, v231, v232
	s_waitcnt lgkmcnt(2)
	v_mfma_f32_32x32x16_bf16 v[98:113], v[218:221], v[174:177], v[66:81]
	ds_read_b128 v[218:221], v205 offset:49152
	v_cvt_pk_bf16_f32 v136, v233, v234
	v_cvt_pk_bf16_f32 v137, v235, v236
	v_lshl_add_u32 v238, s65, 14, v210
	v_permlane32_swap_b32_e32 v134, v136
	v_permlane32_swap_b32_e32 v135, v137
	s_waitcnt lgkmcnt(2)
	v_mfma_f32_32x32x16_bf16 v[146:161], v[222:225], v[170:173], v[146:161]
	ds_read_b128 v[222:225], v205 offset:57344
	v_exp_f32_e32 v237, v138
	v_exp_f32_e32 v239, v143
	v_exp_f32_e32 v240, v144
	v_exp_f32_e32 v241, v145
	v_exp_f32_e32 v242, v114
	v_exp_f32_e32 v243, v115
	s_waitcnt lgkmcnt(2)
	v_mfma_f32_32x32x16_bf16 v[98:113], v[226:229], v[170:173], v[98:113]
	v_exp_f32_e32 v244, v116
	v_exp_f32_e32 v245, v117
	v_cvt_pk_bf16_f32 v117, v240, v241
	v_exp_f32_e32 v246, v118
	v_cvt_pk_bf16_f32 v118, v242, v243
	v_add_f32_e32 v217, 0, v217
	s_waitcnt lgkmcnt(0)
	v_mfma_f32_32x32x16_bf16 v[146:161], v[218:221], v[166:169], v[146:161]
	ds_read_b128 v[130:133], v207 offset:57344
	ds_read_b128 v[218:221], v207 offset:49152
	v_mfma_f32_32x32x16_bf16 v[98:113], v[222:225], v[166:169], v[98:113]
	s_waitcnt lgkmcnt(0)
	v_mfma_f32_32x32x16_bf16 v[146:161], v[218:221], v[162:165], v[146:161]
	ds_read_b64_tr_b16 v[220:221], v238 offset:2048
	v_mfma_f32_32x32x16_bf16 v[98:113], v[130:133], v[162:165], v[98:113]
	ds_read_b64_tr_b16 v[218:219], v238
	ds_read_b64_tr_b16 v[130:131], v238 offset:512
	ds_read_b64_tr_b16 v[222:223], v238 offset:1024
	ds_read_b64_tr_b16 v[226:227], v238 offset:1536
	ds_read_b64_tr_b16 v[132:133], v238 offset:2560
	ds_read_b64_tr_b16 v[224:225], v238 offset:3072
	ds_read_b64_tr_b16 v[228:229], v238 offset:3584
	s_waitcnt lgkmcnt(0)
	v_mfma_f32_32x32x16_bf16 v[50:65], v[134:137], v[218:221], v[50:65]
	v_exp_f32_e32 v218, v139
	v_exp_f32_e32 v219, v140
	v_exp_f32_e32 v220, v141
	v_exp_f32_e32 v221, v142
	v_cvt_pk_bf16_f32 v114, v237, v218
	v_cvt_pk_bf16_f32 v115, v219, v220
	v_cvt_pk_bf16_f32 v116, v221, v239
	v_mfma_f32_32x32x16_bf16 v[34:49], v[134:137], v[130:133], v[34:49]
	s_nop 0
	v_permlane32_swap_b32_e32 v114, v116
	v_permlane32_swap_b32_e32 v115, v117
	ds_read_b64_tr_b16 v[132:133], v238 offset:6144
	v_mfma_f32_32x32x16_bf16 v[18:33], v[134:137], v[222:225], v[18:33]
	v_exp_f32_e32 v222, v119
	v_exp_f32_e32 v223, v120
	v_exp_f32_e32 v224, v121
	v_cvt_pk_bf16_f32 v119, v244, v245
	v_cvt_pk_bf16_f32 v120, v246, v222
	s_nop 1
	v_permlane32_swap_b32_e32 v118, v120
	v_mfma_f32_32x32x16_bf16 v[2:17], v[134:137], v[226:229], v[2:17]
	ds_read_b64_tr_b16 v[130:131], v238 offset:4096
	ds_read_b64_tr_b16 v[134:135], v238 offset:4608
	ds_read_b64_tr_b16 v[138:139], v238 offset:5120
	ds_read_b64_tr_b16 v[142:143], v238 offset:5632
	ds_read_b64_tr_b16 v[136:137], v238 offset:6656
	ds_read_b64_tr_b16 v[140:141], v238 offset:7168
	ds_read_b64_tr_b16 v[144:145], v238 offset:7680
	v_cvt_pk_bf16_f32 v121, v223, v224
	v_exp_f32_e32 v227, v124
	v_exp_f32_e32 v228, v125
	v_permlane32_swap_b32_e32 v119, v121
	ds_read_b64_tr_b16 v[124:125], v238 offset:10240
	s_waitcnt lgkmcnt(0)
; DI void partialSM(f32x16& p0, f32x16& p1, float& m_reg, f32x16& negm, float& alpha) {
;   float pmax = fmaxf(p0[0], p0[1]);
; #pragma unroll
;   for (int r = 2; r < 16; ++r) pmax = fmaxf(pmax, p0[r]);
; #pragma unroll
;   for (int r = 0; r < 16; ++r) pmax = fmaxf(pmax, p1[r]);
;   { auto rr = __builtin_amdgcn_permlane32_swap(__float_as_uint(pmax), __float_as_uint(pmax), false, false);
;     pmax = fmaxf(__uint_as_float(rr[0]), __uint_as_float(rr[1])); }
;   alpha = 1.f;
;   if (__builtin_expect(!__all(pmax <= ATT_THR), 0)) {
;     const float dl = fmaxf(pmax, 0.f); m_reg += dl; alpha = __builtin_amdgcn_exp2f(-dl);
; #pragma unroll
;     for (int r = 0; r < 16; ++r) { p0[r] -= dl; p1[r] -= dl; negm[r] = -m_reg; }
;   }
; #pragma unroll
;   for (int r = 0; r < 16; ++r) p0[r] = __builtin_amdgcn_exp2f(p0[r]);
; }
; DI void finishSM(f32x16& p0, f32x16& p1, float alpha, float& l_reg, s16x8& pa0, s16x8& pa1, s16x8& pa2, s16x8& pa3) {
; #pragma unroll
;   for (int r = 0; r < 16; ++r) p1[r] = __builtin_amdgcn_exp2f(p1[r]);
;   float ps = 0;
; #pragma unroll
;   for (int r = 0; r < 16; ++r) ps += p0[r];
; #pragma unroll
;   for (int r = 0; r < 16; ++r) ps += p1[r];
;   { auto rr = __builtin_amdgcn_permlane32_swap(__float_as_uint(ps), __float_as_uint(ps), false, false);
;     ps = __uint_as_float(rr[0]) + __uint_as_float(rr[1]); }
;   l_reg = l_reg * alpha + ps;
;   PK4(p0, 0, pa0); PK4(p0, 8, pa1); PK4(p1, 0, pa2); PK4(p1, 8, pa3);
; }
; DI void qkt64(f32x16& p0, f32x16& p1, const char* Ks, const s16x8* qr, const f32x16& negm, int comp, int r32, int hi) {
; #pragma unroll
;   for (int d0 = 0; d0 < 4; ++d0) { const int cb = (comp * 64 + d0 * 16 + hi * 8) * 2;
;     const s16x8 b0 = *(const s16x8*)(Ks + KSWZ(r32, cb));
;     const s16x8 b1 = *(const s16x8*)(Ks + KSWZ(32 + r32, cb));
;     if (d0 == 0) { p0 = MFMA32(b0, qr[0], negm); p1 = MFMA32(b1, qr[0], negm); }
;     else { p0 = MFMA32(b0, qr[d0], p0); p1 = MFMA32(b1, qr[d0], p1); } }
; }
; DI void pv_all(f32x16* o, int vb, s16x8 pa0, s16x8 pa1, s16x8 pa2, s16x8 pa3) {
;   const lds_cptr p = (lds_cptr)(uintptr_t)(unsigned)vb;
;   const s16x8 pa[4] = {pa0, pa1, pa2, pa3};
; #pragma unroll
;   for (int ks = 0; ks < 4; ++ks)
; #pragma unroll
;     for (int d0 = 0; d0 < 4; ++d0) { const s16x4 l = vtr(p + v_rd_off(d0, ks, 0)), h = vtr(p + v_rd_off(d0, ks, 1)); o[d0] = MFMA32(pa[ks], PKF(l, h), o[d0]); }
; }
	v_mfma_f32_32x32x16_bf16 v[50:65], v[114:117], v[130:133], v[50:65]
	v_exp_f32_e32 v225, v122
	v_exp_f32_e32 v226, v123
	v_mfma_f32_32x32x16_bf16 v[34:49], v[114:117], v[134:137], v[34:49]
	v_exp_f32_e32 v134, v126
	v_exp_f32_e32 v135, v127
	v_exp_f32_e32 v136, v128
	v_exp_f32_e32 v137, v129
	v_mfma_f32_32x32x16_bf16 v[18:33], v[114:117], v[138:141], v[18:33]
	v_mfma_f32_32x32x16_bf16 v[2:17], v[114:117], v[142:145], v[2:17]
	ds_read_b64_tr_b16 v[122:123], v238 offset:8192
	ds_read_b64_tr_b16 v[114:115], v238 offset:8704
	ds_read_b64_tr_b16 v[126:127], v238 offset:9216
	ds_read_b64_tr_b16 v[130:131], v238 offset:9728
	ds_read_b64_tr_b16 v[116:117], v238 offset:10752
	ds_read_b64_tr_b16 v[128:129], v238 offset:11264
	ds_read_b64_tr_b16 v[132:133], v238 offset:11776
	s_waitcnt lgkmcnt(0)
	v_mfma_f32_32x32x16_bf16 v[50:65], v[118:121], v[122:125], v[50:65]
	v_add_f32_e32 v122, v230, v217
	v_add_f32_e32 v122, v231, v122
	v_add_f32_e32 v122, v232, v122
	v_add_f32_e32 v122, v233, v122
	v_add_f32_e32 v122, v234, v122
	v_add_f32_e32 v122, v235, v122
	v_add_f32_e32 v122, v236, v122
	v_mfma_f32_32x32x16_bf16 v[34:49], v[118:121], v[114:117], v[34:49]
	v_add_f32_e32 v114, v237, v122
	v_cvt_pk_bf16_f32 v122, v225, v226
	v_cvt_pk_bf16_f32 v123, v227, v228
	v_cvt_pk_bf16_f32 v124, v134, v135
	v_cvt_pk_bf16_f32 v125, v136, v137
	v_add_f32_e32 v114, v218, v114
	v_permlane32_swap_b32_e32 v122, v124
	v_permlane32_swap_b32_e32 v123, v125
	v_add_f32_e32 v114, v219, v114
	v_add_f32_e32 v114, v220, v114
	v_add_f32_e32 v114, v221, v114
	v_add_f32_e32 v138, v239, v114
	v_mfma_f32_32x32x16_bf16 v[18:33], v[118:121], v[126:129], v[18:33]
	v_mfma_f32_32x32x16_bf16 v[2:17], v[118:121], v[130:133], v[2:17]
	ds_read_b64_tr_b16 v[116:117], v238 offset:14336
	ds_read_b64_tr_b16 v[114:115], v238 offset:12288
	ds_read_b64_tr_b16 v[118:119], v238 offset:12800
	ds_read_b64_tr_b16 v[126:127], v238 offset:13312
	ds_read_b64_tr_b16 v[130:131], v238 offset:13824
	ds_read_b64_tr_b16 v[120:121], v238 offset:14848
	ds_read_b64_tr_b16 v[128:129], v238 offset:15360
	ds_read_b64_tr_b16 v[132:133], v238 offset:15872
	s_waitcnt lgkmcnt(0)
	v_mfma_f32_32x32x16_bf16 v[50:65], v[122:125], v[114:117], v[50:65]
	v_add_f32_e32 v114, v240, v138
	v_add_f32_e32 v114, v241, v114
	v_add_f32_e32 v114, v242, v114
	v_add_f32_e32 v114, v243, v114
	v_add_f32_e32 v114, v244, v114
	v_add_f32_e32 v114, v245, v114
	v_add_f32_e32 v114, v246, v114
	v_add_f32_e32 v114, v222, v114
	v_add_f32_e32 v114, v223, v114
	v_add_f32_e32 v114, v224, v114
	v_add_f32_e32 v114, v225, v114
	v_add_f32_e32 v114, v226, v114
	v_add_f32_e32 v114, v227, v114
	v_add_f32_e32 v114, v228, v114
	v_add_f32_e32 v114, v134, v114
	v_add_f32_e32 v114, v135, v114
	v_add_f32_e32 v114, v136, v114
	v_add_f32_e32 v115, v137, v114
	v_max_f32_e32 v114, v147, v147
	v_max_f32_e32 v117, v146, v146
	v_max_f32_e32 v114, v117, v114
	v_max3_f32 v114, v114, v148, v149
	v_max3_f32 v114, v114, v150, v151
	v_max3_f32 v114, v114, v152, v153
	v_max3_f32 v114, v114, v154, v155
	v_max3_f32 v114, v114, v156, v157
	v_max3_f32 v114, v114, v158, v159
	v_max3_f32 v114, v114, v160, v161
	v_max3_f32 v114, v114, v98, v99
	v_max3_f32 v114, v114, v100, v101
	v_max3_f32 v114, v114, v102, v103
	v_max3_f32 v114, v114, v104, v105
	v_max3_f32 v114, v114, v106, v107
	v_max3_f32 v114, v114, v108, v109
	v_mfma_f32_32x32x16_bf16 v[34:49], v[122:125], v[118:121], v[34:49]
	v_max3_f32 v114, v114, v110, v111
	v_max3_f32 v114, v114, v112, v113
	v_mov_b32_e32 v117, v114
	s_nop 1
	v_permlane32_swap_b32_e32 v114, v117
	v_max_f32_e32 v117, v117, v117
	v_max_f32_e32 v114, v114, v114
	v_mfma_f32_32x32x16_bf16 v[18:33], v[122:125], v[126:129], v[18:33]
	v_max_f32_e32 v117, v114, v117
	v_mov_b32_e32 v116, v115
	v_cmp_ge_f32_e32 vcc, s58, v117
	s_nop 0
	v_permlane32_swap_b32_e32 v115, v116
	s_cmp_eq_u64 vcc, exec
	v_mov_b32_e32 v114, 1.0
	v_mfma_f32_32x32x16_bf16 v[2:17], v[122:125], v[130:133], v[2:17]
	s_cbranch_scc0 .LBB0_393
	v_cmp_gt_f32_e32 vcc, 1.0, v114
	s_cbranch_vccz .LBB0_390
